# diff attention: conflict-free K tile LDS layout (pitch 320B + 32B skew)
# speedup vs baseline: 1.0102x; 1.0019x over previous
.LBB0_140:
	s_abs_i32 s6, s70
	s_mul_hi_u32 s7, s6, s69
	s_mul_i32 s8, s7, s68
	s_ashr_i32 s0, s70, 31
	s_sub_i32 s8, s6, s8
	s_xor_b32 s1, s0, s62
	s_add_i32 s9, s7, 1
	s_sub_i32 s14, s8, s68
	s_cmp_ge_u32 s8, s68
	s_cselect_b32 s7, s9, s7
	s_cselect_b32 s8, s14, s8
	s_add_i32 s9, s7, 1
	s_cmp_ge_u32 s8, s68
	s_cselect_b32 s7, s9, s7
	s_xor_b32 s7, s7, s1
	s_sub_i32 s8, s7, s1
	s_mul_i32 s1, s8, s13
	s_sub_i32 s9, s70, s1
	s_mul_hi_u32 s1, s6, s84
	s_mul_i32 s7, s1, s23
	s_sub_i32 s6, s6, s7
	s_add_i32 s7, s1, 1
	s_sub_i32 s14, s6, s23
	s_cmp_ge_u32 s6, s23
	s_cselect_b32 s1, s7, s1
	s_cselect_b32 s6, s14, s6
	s_add_i32 s7, s1, 1
	s_cmp_ge_u32 s6, s23
	s_cselect_b32 s1, s7, s1
	s_xor_b32 s1, s1, s0
	s_sub_i32 s0, s1, s0
	s_ashr_i32 s1, s0, 31
	s_lshl_b64 s[6:7], s[0:1], s81
	s_lshl_b32 s1, s9, 7
	s_ashr_i32 s9, s1, 31
	s_add_u32 s6, s6, s1
	s_addc_u32 s7, s7, s9
	s_mul_i32 s1, s7, 0x3600
	s_mul_hi_u32 s9, s6, 0x3600
	s_add_i32 s9, s9, s1
	s_mul_i32 s1, s6, 0x3600
	s_add_u32 s1, s16, s1
	s_addc_u32 s9, s17, s9
	s_lshl_b32 s8, s8, 7
	s_and_b32 s8, s8, 0x180
	s_lshl_b32 s71, s8, 1
	s_add_u32 s14, s1, s71
	s_addc_u32 s15, s9, 0
	s_mul_hi_i32 s1, s47, s0
	s_mul_i32 s0, s47, s0
	s_add_u32 s0, s10, s0
	v_mov_b32_e32 v92, v220
	s_addc_u32 s1, s11, s1
	s_add_u32 s8, s0, s71
	v_ashrrev_i32_e32 v0, 2, v92
	v_bfe_u32 v93, v92, 4, 2
	v_bfi_b32 v202, -16, v0, v92
	v_mov_b64_e32 v[0:1], s[14:15]
	s_addc_u32 s9, s1, 0
	v_mad_i64_i32 v[0:1], s[0:1], v202, s57, v[0:1]
	v_lshlrev_b32_e32 v192, 4, v93
	v_lshl_add_u64 v[12:13], v[0:1], 0, v[192:193]
	global_load_dwordx4 v[0:3], v[12:13], off offset:3072
	s_movk_i32 s0, 0x400
	v_cmp_gt_i32_e32 vcc, s0, v92
	s_movk_i32 s0, 0x200
	v_add_u32_e32 v29, 0x200, v92
	v_bfe_u32 v94, v92, 2, 2
	s_cmp_eq_u64 exec, 0
	s_waitcnt vmcnt(0)
	v_lshlrev_b32_e32 v4, 16, v0
	v_and_b32_e32 v5, 0xffff0000, v0
	v_pk_mul_f32 v[4:5], v[4:5], s[54:55] op_sel_hi:[1,0]
	s_nop 0
	v_cvt_pk_bf16_f32 v0, v4, v5
	v_lshlrev_b32_e32 v4, 16, v1
	v_and_b32_e32 v5, 0xffff0000, v1
	v_pk_mul_f32 v[4:5], v[4:5], s[54:55] op_sel_hi:[1,0]
	s_nop 0
	v_cvt_pk_bf16_f32 v1, v4, v5
	v_lshlrev_b32_e32 v4, 16, v2
	v_and_b32_e32 v5, 0xffff0000, v2
	v_pk_mul_f32 v[4:5], v[4:5], s[54:55] op_sel_hi:[1,0]
	s_nop 0
	v_cvt_pk_bf16_f32 v2, v4, v5
	v_lshlrev_b32_e32 v4, 16, v3
	v_and_b32_e32 v5, 0xffff0000, v3
	v_pk_mul_f32 v[4:5], v[4:5], s[54:55] op_sel_hi:[1,0]
	s_nop 0
	v_cvt_pk_bf16_f32 v3, v4, v5
	global_load_dwordx4 v[4:7], v[12:13], off offset:3136
	s_waitcnt vmcnt(0)
	v_lshlrev_b32_e32 v8, 16, v4
	v_and_b32_e32 v9, 0xffff0000, v4
	v_pk_mul_f32 v[8:9], v[8:9], s[54:55] op_sel_hi:[1,0]
	s_nop 0
	v_cvt_pk_bf16_f32 v4, v8, v9
	v_lshlrev_b32_e32 v8, 16, v5
	v_and_b32_e32 v9, 0xffff0000, v5
	v_pk_mul_f32 v[8:9], v[8:9], s[54:55] op_sel_hi:[1,0]
	s_nop 0
	v_cvt_pk_bf16_f32 v5, v8, v9
	v_lshlrev_b32_e32 v8, 16, v6
	v_and_b32_e32 v9, 0xffff0000, v6
	v_pk_mul_f32 v[8:9], v[8:9], s[54:55] op_sel_hi:[1,0]
	s_nop 0
	v_cvt_pk_bf16_f32 v6, v8, v9
	v_lshlrev_b32_e32 v8, 16, v7
	v_and_b32_e32 v9, 0xffff0000, v7
	v_pk_mul_f32 v[8:9], v[8:9], s[54:55] op_sel_hi:[1,0]
	s_nop 0
	v_cvt_pk_bf16_f32 v7, v8, v9
	global_load_dwordx4 v[8:11], v[12:13], off offset:3200
	s_waitcnt vmcnt(0)
	v_lshlrev_b32_e32 v14, 16, v8
	v_and_b32_e32 v15, 0xffff0000, v8
	v_pk_mul_f32 v[14:15], v[14:15], s[54:55] op_sel_hi:[1,0]
	s_nop 0
	v_cvt_pk_bf16_f32 v8, v14, v15
	v_lshlrev_b32_e32 v14, 16, v9
	v_and_b32_e32 v15, 0xffff0000, v9
	v_pk_mul_f32 v[14:15], v[14:15], s[54:55] op_sel_hi:[1,0]
	s_nop 0
	v_cvt_pk_bf16_f32 v9, v14, v15
	v_lshlrev_b32_e32 v14, 16, v10
	v_and_b32_e32 v15, 0xffff0000, v10
	v_pk_mul_f32 v[14:15], v[14:15], s[54:55] op_sel_hi:[1,0]
	s_nop 0
	v_cvt_pk_bf16_f32 v10, v14, v15
	v_lshlrev_b32_e32 v14, 16, v11
	v_and_b32_e32 v15, 0xffff0000, v11
	v_pk_mul_f32 v[14:15], v[14:15], s[54:55] op_sel_hi:[1,0]
	s_nop 0
	v_cvt_pk_bf16_f32 v11, v14, v15
	global_load_dwordx4 v[12:15], v[12:13], off offset:3264
	s_waitcnt vmcnt(0)
	v_lshlrev_b32_e32 v16, 16, v12
	v_and_b32_e32 v17, 0xffff0000, v12
	v_pk_mul_f32 v[16:17], v[16:17], s[54:55] op_sel_hi:[1,0]
	s_nop 0
	v_cvt_pk_bf16_f32 v12, v16, v17
	v_lshlrev_b32_e32 v16, 16, v13
	v_and_b32_e32 v17, 0xffff0000, v13
	v_pk_mul_f32 v[16:17], v[16:17], s[54:55] op_sel_hi:[1,0]
	s_nop 0
	v_cvt_pk_bf16_f32 v13, v16, v17
	v_lshlrev_b32_e32 v16, 16, v14
	v_and_b32_e32 v17, 0xffff0000, v14
	v_pk_mul_f32 v[16:17], v[16:17], s[54:55] op_sel_hi:[1,0]
	s_nop 0
	v_cvt_pk_bf16_f32 v14, v16, v17
	v_lshlrev_b32_e32 v16, 16, v15
	v_and_b32_e32 v17, 0xffff0000, v15
	v_pk_mul_f32 v[16:17], v[16:17], s[54:55] op_sel_hi:[1,0]
	s_nop 0
	v_cvt_pk_bf16_f32 v15, v16, v17
	v_add_u32_e32 v16, 0xfffffe00, v92
	v_cndmask_b32_e32 v16, v16, v92, vcc
	v_ashrrev_i32_e32 v17, 31, v16
	v_cmp_gt_i32_e32 vcc, s0, v92
	v_lshrrev_b32_e32 v17, 28, v17
	v_add_u32_e32 v17, v16, v17
	v_cndmask_b32_e32 v22, v92, v29, vcc
	v_ashrrev_i32_e32 v23, 31, v22
	v_ashrrev_i32_e32 v204, 4, v17
	v_and_b32_e32 v17, -16, v17
	v_lshrrev_b32_e32 v23, 28, v23
	v_sub_u32_e32 v28, v16, v17
	v_ashrrev_i32_e32 v205, 31, v204
	v_add_u32_e32 v23, v22, v23
	v_lshlrev_b64 v[16:17], 11, v[204:205]
	v_lshlrev_b32_e32 v84, 3, v28
	v_ashrrev_i32_e32 v206, 4, v23
	v_and_b32_e32 v23, -16, v23
	v_lshl_add_u64 v[16:17], s[8:9], 0, v[16:17]
	v_ashrrev_i32_e32 v85, 31, v84
	v_sub_u32_e32 v30, v22, v23
	v_ashrrev_i32_e32 v207, 31, v206
	v_lshl_add_u64 v[20:21], v[84:85], 1, v[16:17]
	v_lshlrev_b64 v[22:23], 11, v[206:207]
	v_lshlrev_b32_e32 v86, 3, v30
	global_load_dwordx4 v[16:19], v[20:21], off
	v_lshl_add_u64 v[22:23], s[8:9], 0, v[22:23]
	v_ashrrev_i32_e32 v87, 31, v86
	v_lshl_add_u64 v[22:23], v[86:87], 1, v[22:23]
	global_load_dwordx4 v[24:27], v[22:23], off
	v_mul_u32_u24_e32 v205, 0x140, v204
	v_and_b32_e32 v255, 16, v204
	v_lshl_add_u32 v205, v255, 1, v205
	v_lshlrev_b32_e32 v207, 4, v28
	v_add3_u32 v42, 0, v205, v207
	v_mul_u32_u24_e32 v227, 0x140, v206
	v_and_b32_e32 v255, 16, v206
	v_lshl_add_u32 v227, v255, 1, v227
	v_lshlrev_b32_e32 v228, 4, v30
	v_add3_u32 v43, 0, v227, v228
	s_mov_b32 s0, 0x40000
	s_waitcnt vmcnt(1)
	ds_write_b128 v42, v[16:19] offset:36864
	v_add_co_u32_e32 v16, vcc, s33, v20
	s_nop 1
	v_addc_co_u32_e32 v17, vcc, 0, v21, vcc
	global_load_dwordx4 v[16:19], v[16:17], off
	s_waitcnt vmcnt(1)
	ds_write_b128 v43, v[24:27] offset:36864
	v_ashrrev_i32_e32 v26, 31, v29
	v_lshrrev_b32_e32 v26, 28, v26
	v_add_u32_e32 v26, v29, v26
	v_ashrrev_i32_e32 v210, 4, v26
	v_and_b32_e32 v26, -16, v26
	v_sub_u32_e32 v45, v29, v26
	v_ashrrev_i32_e32 v211, 31, v210
	v_lshlrev_b64 v[26:27], 11, v[210:211]
	v_lshlrev_b32_e32 v90, 3, v45
	v_add_co_u32_e32 v24, vcc, s33, v22
	v_lshl_add_u64 v[26:27], s[8:9], 0, v[26:27]
	v_ashrrev_i32_e32 v91, 31, v90
	v_addc_co_u32_e32 v25, vcc, 0, v23, vcc
	v_lshl_add_u64 v[28:29], v[90:91], 1, v[26:27]
	global_load_dwordx4 v[30:33], v[24:25], off
	global_load_dwordx4 v[38:41], v[28:29], off offset:1024
	v_ashrrev_i32_e32 v24, 31, v92
	v_lshrrev_b32_e32 v24, 28, v24
	v_add_u32_e32 v24, v92, v24
	v_ashrrev_i32_e32 v208, 4, v24
	v_and_b32_e32 v24, -16, v24
	v_sub_u32_e32 v44, v92, v24
	v_ashrrev_i32_e32 v209, 31, v208
	v_lshlrev_b64 v[24:25], 11, v[208:209]
	v_lshlrev_b32_e32 v88, 3, v44
	v_lshl_add_u64 v[24:25], s[8:9], 0, v[24:25]
	v_ashrrev_i32_e32 v89, 31, v88
	v_lshl_add_u64 v[24:25], v[88:89], 1, v[24:25]
	global_load_dwordx4 v[34:37], v[24:25], off offset:1024
	s_waitcnt vmcnt(3)
	ds_write_b128 v42, v[16:19]
	s_waitcnt vmcnt(2)
	ds_write_b128 v43, v[30:33]
	v_lshrrev_b32_e32 v17, 1, v208
	v_and_b32_e32 v16, 3, v208
	v_and_b32_e32 v17, 4, v17
	v_lshrrev_b32_e32 v19, 1, v44
	v_bitop3_b32 v16, v17, v19, v16 bitop3:0x36
	v_lshlrev_b32_e32 v209, 8, v208
	v_lshlrev_b32_e32 v211, 5, v16
	v_lshlrev_b32_e32 v16, 4, v44
	v_add_u32_e32 v18, 0, v209
	v_and_b32_e32 v229, 16, v16
	v_add3_u32 v16, v18, v211, v229
	v_lshrrev_b32_e32 v17, 1, v210
	v_and_b32_e32 v17, 4, v17
	v_lshrrev_b32_e32 v19, 1, v45
	s_waitcnt vmcnt(0)
	ds_write_b128 v16, v[34:37] offset:20480
	v_and_b32_e32 v16, 3, v210
	v_bitop3_b32 v16, v17, v19, v16 bitop3:0x36
	v_lshlrev_b32_e32 v230, 8, v210
	v_lshlrev_b32_e32 v231, 5, v16
	v_lshlrev_b32_e32 v16, 4, v45
	v_add_u32_e32 v18, 0, v230
	v_and_b32_e32 v232, 16, v16
	v_add3_u32 v16, v18, v231, v232
	ds_write_b128 v16, v[38:41] offset:20480
	v_add_co_u32_e32 v16, vcc, s0, v20
	v_and_b32_e32 v32, 3, v92
	s_nop 0
	v_addc_co_u32_e32 v17, vcc, 0, v21, vcc
	v_add_co_u32_e32 v20, vcc, s0, v22
	global_load_dwordx4 v[16:19], v[16:17], off
	s_nop 0
	v_addc_co_u32_e32 v21, vcc, 0, v23, vcc
	v_add_co_u32_e32 v24, vcc, s33, v24
	global_load_dwordx4 v[20:23], v[20:21], off
	s_nop 0
	v_addc_co_u32_e32 v25, vcc, 0, v25, vcc
	v_add_co_u32_e32 v28, vcc, s33, v28
	global_load_dwordx4 v[24:27], v[24:25], off offset:1024
	s_nop 0
	v_addc_co_u32_e32 v29, vcc, 0, v29, vcc
	global_load_dwordx4 v[28:31], v[28:29], off offset:1024
	v_lshl_or_b32 v32, v94, 3, v32
	v_mul_u32_u24_e32 v233, 0x140, v32
	v_and_b32_e32 v255, 16, v32
	v_lshl_add_u32 v233, v255, 1, v233
	s_waitcnt lgkmcnt(0)
	s_barrier
	v_add3_u32 v95, 0, v192, v233
	ds_read_b128 v[32:35], v95 offset:36864
	ds_read_b128 v[36:39], v95 offset:36992
	ds_read_b128 v[40:43], v95 offset:38144
	ds_read_b128 v[44:47], v95 offset:38272
	ds_read_b128 v[48:51], v95 offset:47104
	ds_read_b128 v[52:55], v95 offset:47232
	s_waitcnt lgkmcnt(1)
	v_mfma_f32_16x16x32_bf16 v[64:67], v[48:51], v[0:3], 0
	s_waitcnt lgkmcnt(0)
	v_mfma_f32_16x16x32_bf16 v[72:75], v[52:55], v[8:11], 0
	ds_read_b128 v[48:51], v95 offset:48384
	ds_read_b128 v[52:55], v95 offset:48512
	s_waitcnt lgkmcnt(1)
	v_mfma_f32_16x16x32_bf16 v[76:79], v[48:51], v[0:3], 0
	ds_read_b128 v[48:51], v95 offset:36928
	ds_read_b128 v[56:59], v95 offset:37056
	v_mfma_f32_16x16x32_bf16 v[32:35], v[32:35], v[0:3], 0
	v_mfma_f32_16x16x32_bf16 v[36:39], v[36:39], v[8:11], 0
	s_waitcnt lgkmcnt(2)
	v_mfma_f32_16x16x32_bf16 v[80:83], v[52:55], v[8:11], 0
	s_waitcnt lgkmcnt(1)
	v_mfma_f32_16x16x32_bf16 v[52:55], v[48:51], v[4:7], v[32:35]
	s_waitcnt lgkmcnt(0)
	v_mfma_f32_16x16x32_bf16 v[48:51], v[56:59], v[12:15], v[36:39]
	s_nop 0
	ds_read_b128 v[32:35], v95 offset:38208
	s_nop 0
	ds_read_b128 v[36:39], v95 offset:38336
	v_mfma_f32_16x16x32_bf16 v[40:43], v[40:43], v[0:3], 0
	v_mfma_f32_16x16x32_bf16 v[44:47], v[44:47], v[8:11], 0
	s_waitcnt lgkmcnt(1)
	v_mfma_f32_16x16x32_bf16 v[56:59], v[32:35], v[4:7], v[40:43]
	s_waitcnt lgkmcnt(0)
	v_mfma_f32_16x16x32_bf16 v[60:63], v[36:39], v[12:15], v[44:47]
	ds_read_b128 v[32:35], v95 offset:47168
	ds_read_b128 v[36:39], v95 offset:47296
	s_waitcnt lgkmcnt(1)
	v_mfma_f32_16x16x32_bf16 v[68:71], v[32:35], v[4:7], v[64:67]
	s_waitcnt lgkmcnt(0)
	v_mfma_f32_16x16x32_bf16 v[64:67], v[36:39], v[12:15], v[72:75]
	ds_read_b128 v[32:35], v95 offset:48448
	ds_read_b128 v[36:39], v95 offset:48576
	s_waitcnt lgkmcnt(1)
	v_mfma_f32_16x16x32_bf16 v[72:75], v[32:35], v[4:7], v[76:79]
	v_max_f32_e32 v32, v53, v53
	v_max_f32_e32 v33, v52, v52
	v_max_f32_e32 v32, v33, v32
	v_max3_f32 v32, v32, v54, v55
	v_max3_f32 v32, v32, v56, v57
	v_max3_f32 v32, v32, v58, v59
	v_max3_f32 v32, v32, v68, v69
	v_max3_f32 v32, v32, v70, v71
	v_max3_f32 v32, v32, v72, v73
	v_max3_f32 v32, v32, v74, v75
	v_mov_b32_e32 v33, v32
	s_nop 1
	v_permlane16_swap_b32_e32 v32, v33
	s_waitcnt lgkmcnt(0)
	v_mfma_f32_16x16x32_bf16 v[76:79], v[36:39], v[12:15], v[80:83]
	v_max_f32_e32 v33, v33, v33
	v_max_f32_e32 v32, v32, v32
	v_max_f32_e32 v32, v32, v33
	v_mov_b32_e32 v33, v32
	s_nop 1
	v_permlane32_swap_b32_e32 v32, v33
	s_cbranch_scc1 .LBB0_142
	v_max_f32_e32 v32, v32, v32
	v_max_f32_e32 v33, v33, v33
	v_max_f32_e32 v36, v32, v33
	v_exp_f32_e64 v32, -v36
	v_sub_f32_e32 v40, 0, v36
	v_sub_f32_e32 v55, v55, v36
	v_sub_f32_e32 v54, v54, v36
	v_mul_f32_e32 v32, 0, v32
	v_mov_b32_e32 v33, v32
	v_mov_b32_e32 v34, v32
	v_mov_b32_e32 v35, v32
	v_sub_f32_e32 v53, v53, v36
	v_sub_f32_e32 v52, v52, v36
	v_sub_f32_e32 v59, v59, v36
	v_sub_f32_e32 v58, v58, v36
	v_sub_f32_e32 v57, v57, v36
	v_sub_f32_e32 v56, v56, v36
	v_sub_f32_e32 v71, v71, v36
	v_sub_f32_e32 v70, v70, v36
	v_sub_f32_e32 v69, v69, v36
	v_sub_f32_e32 v68, v68, v36
	v_sub_f32_e32 v75, v75, v36
	v_sub_f32_e32 v74, v74, v36
	v_sub_f32_e32 v73, v73, v36
	v_sub_f32_e32 v72, v72, v36
	v_mov_b32_e32 v41, v40
	v_mov_b32_e32 v42, v40
	v_mov_b32_e32 v43, v40
	s_branch .LBB0_143

.LBB0_147:
	s_bitcmp1_b32 s1, 0
	s_cselect_b32 s0, 0x9000, 0
	s_add_i32 s0, s0, 0
	v_add_u32_e32 v128, s0, v235
	v_add3_u32 v128, v128, v236, v237
	v_xor_b32_e32 v129, 32, v238
	v_add_u32_e32 v245, v128, v129
	v_xor_b32_e32 v129, 64, v238
	v_add_u32_e32 v244, v128, v129
	v_xor_b32_e32 v129, 0x60, v238
	v_add_u32_e32 v243, v128, v129
	v_xor_b32_e32 v129, 0x80, v238
	v_add_u32_e32 v242, v128, v129
	v_xor_b32_e32 v129, 0xa0, v238
	s_andn2_b32 s8, 1, s1
	v_add_u32_e32 v241, v128, v129
	v_xor_b32_e32 v129, 0xc0, v238
	s_mul_i32 s8, s8, 0x9000
	v_add_u32_e32 v240, v128, v129
	v_xor_b32_e32 v129, 0xe0, v238
	s_add_i32 s8, s8, 0
	v_add_u32_e32 v246, v128, v238
	v_add_u32_e32 v239, v128, v129
	v_add3_u32 v160, s8, v205, v207
	ds_read_b64_tr_b16 v[156:157], v246 offset:20480
	ds_read_b64_tr_b16 v[158:159], v246 offset:21504
	ds_read_b64_tr_b16 v[152:153], v245 offset:20480
	ds_read_b64_tr_b16 v[154:155], v245 offset:21504
	ds_read_b64_tr_b16 v[148:149], v244 offset:20480
	ds_read_b64_tr_b16 v[150:151], v244 offset:21504
	ds_read_b64_tr_b16 v[144:145], v243 offset:20480
	ds_read_b64_tr_b16 v[146:147], v243 offset:21504
	ds_read_b64_tr_b16 v[140:141], v242 offset:20480
	ds_read_b64_tr_b16 v[142:143], v242 offset:21504
	ds_read_b64_tr_b16 v[136:137], v241 offset:20480
	ds_read_b64_tr_b16 v[138:139], v241 offset:21504
	ds_read_b64_tr_b16 v[132:133], v240 offset:20480
	ds_read_b64_tr_b16 v[134:135], v240 offset:21504
	ds_read_b64_tr_b16 v[128:129], v239 offset:20480
	ds_read_b64_tr_b16 v[130:131], v239 offset:21504
	s_waitcnt vmcnt(3)
	ds_write_b128 v160, v[16:19]
	v_add3_u32 v16, s8, v227, v228
	s_waitcnt vmcnt(2)
	ds_write_b128 v16, v[20:23]
	v_add_u32_e32 v16, s8, v209
	v_add3_u32 v16, v16, v211, v229
	s_waitcnt vmcnt(1)
	ds_write_b128 v16, v[24:27] offset:20480
	v_add_u32_e32 v16, s8, v230
	v_add3_u32 v16, v16, v231, v232
	s_waitcnt vmcnt(0)
	ds_write_b128 v16, v[28:31] offset:20480
	v_add3_u32 v247, s0, v192, v233
	ds_read_b128 v[20:23], v247
	ds_read_b128 v[188:191], v247 offset:64
	ds_read_b128 v[24:27], v247 offset:128
	s_waitcnt lgkmcnt(2)
	v_mfma_f32_16x16x32_bf16 v[160:163], v[20:23], v[0:3], v[40:43]
	ds_read_b128 v[28:31], v247 offset:1280
	s_add_i32 s8, s1, 3
	s_add_i32 s0, s1, 2
	s_waitcnt lgkmcnt(2)
	v_mfma_f32_16x16x32_bf16 v[188:191], v[188:191], v[4:7], v[160:163]
	s_min_u32 s8, s8, s83
	s_min_u32 s0, s0, s83
	s_lshl_b32 s8, s8, 6
	ds_read_b128 v[160:163], v247 offset:192
	s_waitcnt lgkmcnt(2)
	v_mfma_f32_16x16x32_bf16 v[168:171], v[24:27], v[8:11], v[44:47]
	ds_read_b128 v[24:27], v247 offset:10240
	s_lshl_b32 s0, s0, 6
	v_add_u32_e32 v16, s8, v204
	s_waitcnt lgkmcnt(1)
	v_mfma_f32_16x16x32_bf16 v[160:163], v[160:163], v[12:15], v[168:171]
	s_nop 2
	ds_read_b128 v[168:171], v247 offset:1344
	v_add_u32_e32 v164, s8, v206
	v_add_u32_e32 v184, s0, v208
	v_mfma_f32_16x16x32_bf16 v[172:175], v[28:31], v[0:3], v[40:43]
	ds_read_b128 v[28:31], v247 offset:10368
	v_ashrrev_i32_e32 v17, 31, v16
	v_ashrrev_i32_e32 v165, 31, v164
	s_waitcnt lgkmcnt(0)
	v_mfma_f32_16x16x32_bf16 v[248:251], v[28:31], v[8:11], v[44:47]
	v_add_u32_e32 v28, s0, v210
	v_ashrrev_i32_e32 v185, 31, v184
	v_ashrrev_i32_e32 v29, 31, v28
	v_lshlrev_b64 v[16:17], 11, v[16:17]
	v_lshlrev_b64 v[20:21], 11, v[164:165]
	v_mfma_f32_16x16x32_bf16 v[180:183], v[24:27], v[0:3], v[40:43]
	v_lshlrev_b64 v[24:25], 11, v[184:185]
	v_lshlrev_b64 v[28:29], 11, v[28:29]
	v_lshl_add_u64 v[16:17], v[212:213], 0, v[16:17]
	v_lshl_add_u64 v[20:21], v[214:215], 0, v[20:21]
	v_lshl_add_u64 v[24:25], v[216:217], 0, v[24:25]
	v_lshl_add_u64 v[28:29], v[218:219], 0, v[28:29]
	global_load_dwordx4 v[16:19], v[16:17], off
	ds_read_b128 v[184:187], v247 offset:11648
	global_load_dwordx4 v[20:23], v[20:21], off
	ds_read_b128 v[164:167], v247 offset:1408
	global_load_dwordx4 v[24:27], v[24:25], off offset:1024
	s_waitcnt lgkmcnt(1)
	v_mfma_f32_16x16x32_bf16 v[194:197], v[184:187], v[8:11], v[44:47]
	global_load_dwordx4 v[28:31], v[28:29], off offset:1024
	ds_read_b128 v[176:179], v247 offset:11520
	s_add_i32 s8, s1, 1
	v_mfma_f32_16x16x32_bf16 v[184:187], v[168:171], v[4:7], v[172:175]
	ds_read_b128 v[168:171], v247 offset:1472
	s_cmp_ge_u32 s8, s82
	s_waitcnt lgkmcnt(2)
	v_mfma_f32_16x16x32_bf16 v[164:167], v[164:167], v[8:11], v[44:47]
	ds_read_b128 v[172:175], v247 offset:11584
	s_waitcnt lgkmcnt(1)
	v_mfma_f32_16x16x32_bf16 v[168:171], v[168:171], v[12:15], v[164:167]
	s_nop 4
	ds_read_b128 v[164:167], v247 offset:10304
	s_waitcnt lgkmcnt(0)
	v_mfma_f32_16x16x32_bf16 v[180:183], v[164:167], v[4:7], v[180:183]
	ds_read_b128 v[164:167], v247 offset:10432
	v_mfma_f32_16x16x32_bf16 v[176:179], v[176:179], v[0:3], v[40:43]
	v_mfma_f32_16x16x32_bf16 v[172:175], v[172:175], v[4:7], v[176:179]
	s_waitcnt lgkmcnt(0)
	v_mfma_f32_16x16x32_bf16 v[164:167], v[164:167], v[12:15], v[248:251]
	s_nop 4
	ds_read_b128 v[176:179], v247 offset:11712
	s_waitcnt lgkmcnt(0)
	v_mfma_f32_16x16x32_bf16 v[176:179], v[176:179], v[12:15], v[194:197]
	s_cbranch_scc1 .LBB0_153
	s_cmp_lg_u32 s1, 0
	s_cselect_b64 s[0:1], -1, 0
	s_and_b32 s9, s8, 3
	s_cmp_lg_u32 s9, 0
	s_cselect_b64 s[14:15], -1, 0
	s_and_b64 s[0:1], s[0:1], s[14:15]
	s_and_b64 vcc, exec, s[0:1]
	s_cbranch_vccnz .LBB0_153
	v_max_f32_e32 v194, v189, v189
	v_max_f32_e32 v195, v188, v188
	v_max_f32_e32 v194, v195, v194
	v_max3_f32 v194, v194, v190, v191
	v_max3_f32 v194, v194, v184, v185
	v_max3_f32 v194, v194, v186, v187
	v_max3_f32 v194, v194, v180, v181
	v_max3_f32 v194, v194, v182, v183
	v_max3_f32 v194, v194, v172, v173
	v_max3_f32 v194, v194, v174, v175
	v_mov_b32_e32 v195, v194
	s_nop 1
	v_permlane16_swap_b32_e32 v194, v195
	v_max_f32_e32 v195, v195, v195
	v_max_f32_e32 v194, v194, v194
	v_max_f32_e32 v194, v194, v195
	v_mov_b32_e32 v195, v194
	s_nop 1
	v_permlane32_swap_b32_e32 v194, v195
	v_max_f32_e32 v195, v195, v195
	v_max_f32_e32 v194, v194, v194
	v_max_f32_e32 v247, v194, v195
	v_cmp_lt_f32_e32 vcc, s44, v247
	s_cbranch_vccz .LBB0_151
	s_nop 0
	v_cndmask_b32_e32 v247, 0, v247, vcc
	v_exp_f32_e64 v194, -v247
	v_lshlrev_b32_e32 v196, 16, v72
	v_and_b32_e32 v197, 0xffff0000, v72
	v_sub_f32_e32 v191, v191, v247
	v_pk_mul_f32 v[196:197], v[194:195], v[196:197] op_sel_hi:[0,1]
	v_cvt_pk_bf16_f32 v72, v196, v197
	v_lshlrev_b32_e32 v196, 16, v73
	v_and_b32_e32 v197, 0xffff0000, v73
	v_pk_mul_f32 v[196:197], v[194:195], v[196:197] op_sel_hi:[0,1]
	v_cvt_pk_bf16_f32 v73, v196, v197
	v_lshlrev_b32_e32 v196, 16, v74
	v_and_b32_e32 v197, 0xffff0000, v74
	v_pk_mul_f32 v[196:197], v[194:195], v[196:197] op_sel_hi:[0,1]
	v_cvt_pk_bf16_f32 v74, v196, v197
	v_lshlrev_b32_e32 v196, 16, v75
	v_and_b32_e32 v197, 0xffff0000, v75
	v_pk_mul_f32 v[196:197], v[194:195], v[196:197] op_sel_hi:[0,1]
	v_cvt_pk_bf16_f32 v75, v196, v197
	v_lshlrev_b32_e32 v196, 16, v56
	v_and_b32_e32 v197, 0xffff0000, v56
	v_pk_mul_f32 v[196:197], v[194:195], v[196:197] op_sel_hi:[0,1]
	v_cvt_pk_bf16_f32 v56, v196, v197
	v_lshlrev_b32_e32 v196, 16, v57
	v_and_b32_e32 v197, 0xffff0000, v57
	v_pk_mul_f32 v[196:197], v[194:195], v[196:197] op_sel_hi:[0,1]
	v_cvt_pk_bf16_f32 v57, v196, v197
	v_lshlrev_b32_e32 v196, 16, v58
	v_and_b32_e32 v197, 0xffff0000, v58
	v_pk_mul_f32 v[196:197], v[194:195], v[196:197] op_sel_hi:[0,1]
	v_cvt_pk_bf16_f32 v58, v196, v197
	v_lshlrev_b32_e32 v196, 16, v59
	v_and_b32_e32 v197, 0xffff0000, v59
	v_pk_mul_f32 v[110:111], v[110:111], v[194:195] op_sel_hi:[1,0]
	v_pk_mul_f32 v[108:109], v[108:109], v[194:195] op_sel_hi:[1,0]
	v_pk_mul_f32 v[122:123], v[122:123], v[194:195] op_sel_hi:[1,0]
	v_pk_mul_f32 v[120:121], v[120:121], v[194:195] op_sel_hi:[1,0]
	v_pk_mul_f32 v[114:115], v[114:115], v[194:195] op_sel_hi:[1,0]
	v_pk_mul_f32 v[112:113], v[112:113], v[194:195] op_sel_hi:[1,0]
	v_pk_mul_f32 v[98:99], v[98:99], v[194:195] op_sel_hi:[1,0]
	v_pk_mul_f32 v[96:97], v[96:97], v[194:195] op_sel_hi:[1,0]
	v_pk_mul_f32 v[86:87], v[86:87], v[194:195] op_sel_hi:[1,0]
	v_pk_mul_f32 v[84:85], v[84:85], v[194:195] op_sel_hi:[1,0]
	v_pk_mul_f32 v[70:71], v[70:71], v[194:195] op_sel_hi:[1,0]
	v_pk_mul_f32 v[68:69], v[68:69], v[194:195] op_sel_hi:[1,0]
	v_pk_mul_f32 v[62:63], v[62:63], v[194:195] op_sel_hi:[1,0]
	v_pk_mul_f32 v[60:61], v[60:61], v[194:195] op_sel_hi:[1,0]
	v_pk_mul_f32 v[50:51], v[50:51], v[194:195] op_sel_hi:[1,0]
	v_pk_mul_f32 v[48:49], v[48:49], v[194:195] op_sel_hi:[1,0]
	v_pk_mul_f32 v[34:35], v[34:35], v[194:195] op_sel_hi:[1,0]
	v_pk_mul_f32 v[32:33], v[32:33], v[194:195] op_sel_hi:[1,0]
	v_pk_mul_f32 v[194:195], v[194:195], v[196:197] op_sel_hi:[0,1]
	v_sub_f32_e32 v190, v190, v247
	v_sub_f32_e32 v189, v189, v247
	v_sub_f32_e32 v188, v188, v247
	v_sub_f32_e32 v187, v187, v247
	v_sub_f32_e32 v186, v186, v247
	v_sub_f32_e32 v185, v185, v247
	v_sub_f32_e32 v184, v184, v247
	v_sub_f32_e32 v183, v183, v247
	v_sub_f32_e32 v182, v182, v247
	v_sub_f32_e32 v181, v181, v247
	v_sub_f32_e32 v180, v180, v247
	v_sub_f32_e32 v175, v175, v247
	v_sub_f32_e32 v174, v174, v247
	v_sub_f32_e32 v173, v173, v247
	v_sub_f32_e32 v172, v172, v247
	v_cvt_pk_bf16_f32 v59, v194, v195
	v_sub_f32_e32 v43, v43, v247
	v_sub_f32_e32 v42, v42, v247
	v_sub_f32_e32 v41, v41, v247
	v_sub_f32_e32 v40, v40, v247

.LBB0_153:
	v_mfma_f32_16x16x32_bf16 v[120:123], v[156:159], v[72:75], v[120:123]
	v_exp_f32_e32 v188, v188
	v_exp_f32_e32 v189, v189
	v_mfma_f32_16x16x32_bf16 v[124:127], v[156:159], v[100:103], v[124:127]
	ds_read_b64_tr_b16 v[156:157], v246 offset:28672
	ds_read_b64_tr_b16 v[158:159], v246 offset:29696
	v_mfma_f32_16x16x32_bf16 v[112:115], v[152:155], v[72:75], v[112:115]
	v_exp_f32_e32 v190, v190
	v_exp_f32_e32 v191, v191
	v_mfma_f32_16x16x32_bf16 v[116:119], v[152:155], v[100:103], v[116:119]
	ds_read_b64_tr_b16 v[152:153], v245 offset:28672
	ds_read_b64_tr_b16 v[154:155], v245 offset:29696
	v_mfma_f32_16x16x32_bf16 v[96:99], v[148:151], v[72:75], v[96:99]
	v_exp_f32_e32 v184, v184
	v_exp_f32_e32 v185, v185
	v_mfma_f32_16x16x32_bf16 v[104:107], v[148:151], v[100:103], v[104:107]
	ds_read_b64_tr_b16 v[148:149], v244 offset:28672
	ds_read_b64_tr_b16 v[150:151], v244 offset:29696
	v_mfma_f32_16x16x32_bf16 v[84:87], v[144:147], v[72:75], v[84:87]
	v_exp_f32_e32 v186, v186
	v_exp_f32_e32 v187, v187
	v_mfma_f32_16x16x32_bf16 v[88:91], v[144:147], v[100:103], v[88:91]
	ds_read_b64_tr_b16 v[144:145], v243 offset:28672
	ds_read_b64_tr_b16 v[146:147], v243 offset:29696
	v_mfma_f32_16x16x32_bf16 v[68:71], v[140:143], v[72:75], v[68:71]
	v_exp_f32_e32 v194, v180
	v_exp_f32_e32 v195, v181
	v_mfma_f32_16x16x32_bf16 v[76:79], v[140:143], v[100:103], v[76:79]
	ds_read_b64_tr_b16 v[140:141], v242 offset:28672
	ds_read_b64_tr_b16 v[142:143], v242 offset:29696
	v_mfma_f32_16x16x32_bf16 v[60:63], v[136:139], v[72:75], v[60:63]
	v_exp_f32_e32 v196, v182
	v_exp_f32_e32 v197, v183
	v_mfma_f32_16x16x32_bf16 v[64:67], v[136:139], v[100:103], v[64:67]
	ds_read_b64_tr_b16 v[136:137], v241 offset:28672
	ds_read_b64_tr_b16 v[138:139], v241 offset:29696
	v_mfma_f32_16x16x32_bf16 v[48:51], v[132:135], v[72:75], v[48:51]
	v_exp_f32_e32 v172, v172
	v_exp_f32_e32 v173, v173
	v_mfma_f32_16x16x32_bf16 v[52:55], v[132:135], v[100:103], v[52:55]
	ds_read_b64_tr_b16 v[132:133], v240 offset:28672
	ds_read_b64_tr_b16 v[134:135], v240 offset:29696
	s_mov_b32 s30, s28
	s_mov_b32 s31, s28
	v_mfma_f32_16x16x32_bf16 v[32:35], v[128:131], v[72:75], v[32:35]
	s_mov_b32 s29, s28
	ds_read_b64_tr_b16 v[180:181], v239 offset:28672
	ds_read_b64_tr_b16 v[182:183], v239 offset:29696
	v_exp_f32_e32 v174, v174
	v_mfma_f32_16x16x32_bf16 v[36:39], v[128:131], v[100:103], v[36:39]
	v_mov_b64_e32 v[130:131], s[30:31]
	v_mov_b64_e32 v[128:129], s[28:29]
	v_exp_f32_e32 v175, v175
	s_nop 0
	v_mfma_f32_16x16x32_bf16 v[108:111], v[128:131], v[72:75], v[108:111]
	v_mfma_f32_16x16x32_bf16 v[92:95], v[128:131], v[100:103], v[92:95]
	s_waitcnt lgkmcnt(14)
	v_mfma_f32_16x16x32_bf16 v[120:123], v[156:159], v[56:59], v[120:123]
	v_exp_f32_e32 v100, v160
	v_exp_f32_e32 v101, v161
	v_cvt_pk_bf16_f32 v72, v188, v189
	v_mfma_f32_16x16x32_bf16 v[124:127], v[156:159], v[80:83], v[124:127]
	v_cvt_pk_bf16_f32 v73, v190, v191
	v_cvt_pk_bf16_f32 v74, v184, v185
	v_cvt_pk_bf16_f32 v75, v186, v187
	s_waitcnt lgkmcnt(12)
	v_mfma_f32_16x16x32_bf16 v[112:115], v[152:155], v[56:59], v[112:115]
	v_exp_f32_e32 v102, v162
	v_exp_f32_e32 v103, v163
	v_mfma_f32_16x16x32_bf16 v[116:119], v[152:155], v[80:83], v[116:119]
	s_waitcnt lgkmcnt(10)
	v_mfma_f32_16x16x32_bf16 v[96:99], v[148:151], v[56:59], v[96:99]
	v_exp_f32_e32 v152, v168
	v_exp_f32_e32 v153, v169
	v_mfma_f32_16x16x32_bf16 v[104:107], v[148:151], v[80:83], v[104:107]
	s_waitcnt lgkmcnt(8)
	v_mfma_f32_16x16x32_bf16 v[84:87], v[144:147], v[56:59], v[84:87]
	v_exp_f32_e32 v148, v170
	v_exp_f32_e32 v149, v171
	v_mfma_f32_16x16x32_bf16 v[88:91], v[144:147], v[80:83], v[88:91]
	s_waitcnt lgkmcnt(6)
	v_mfma_f32_16x16x32_bf16 v[68:71], v[140:143], v[56:59], v[68:71]
	v_cvt_pk_bf16_f32 v100, v100, v101
	v_cvt_pk_bf16_f32 v101, v102, v103
	v_cvt_pk_bf16_f32 v102, v152, v153
	v_mfma_f32_16x16x32_bf16 v[76:79], v[140:143], v[80:83], v[76:79]
	v_cvt_pk_bf16_f32 v103, v148, v149
	v_exp_f32_e32 v140, v164
	v_exp_f32_e32 v141, v165
	s_waitcnt lgkmcnt(4)
	v_mfma_f32_16x16x32_bf16 v[60:63], v[136:139], v[56:59], v[60:63]
	v_exp_f32_e32 v142, v166
	v_exp_f32_e32 v143, v167
	v_mfma_f32_16x16x32_bf16 v[64:67], v[136:139], v[80:83], v[64:67]
	s_waitcnt lgkmcnt(2)
	v_mfma_f32_16x16x32_bf16 v[48:51], v[132:135], v[56:59], v[48:51]
	v_exp_f32_e32 v136, v176
	v_exp_f32_e32 v137, v177
	v_mfma_f32_16x16x32_bf16 v[52:55], v[132:135], v[80:83], v[52:55]
	s_waitcnt lgkmcnt(0)
	v_mfma_f32_16x16x32_bf16 v[32:35], v[180:183], v[56:59], v[32:35]
	v_exp_f32_e32 v132, v178
	v_exp_f32_e32 v133, v179
	v_mfma_f32_16x16x32_bf16 v[36:39], v[180:183], v[80:83], v[36:39]
	v_mfma_f32_16x16x32_bf16 v[108:111], v[128:131], v[56:59], v[108:111]
	v_mfma_f32_16x16x32_bf16 v[92:95], v[128:131], v[80:83], v[92:95]
	s_waitcnt lgkmcnt(0)
	s_barrier
	v_cvt_pk_bf16_f32 v56, v194, v195
	v_cvt_pk_bf16_f32 v57, v196, v197
	v_cvt_pk_bf16_f32 v58, v172, v173
	v_cvt_pk_bf16_f32 v59, v174, v175
	v_cvt_pk_bf16_f32 v80, v140, v141
	v_cvt_pk_bf16_f32 v81, v142, v143
	v_cvt_pk_bf16_f32 v82, v136, v137
	v_cvt_pk_bf16_f32 v83, v132, v133
	s_cmp_lg_u32 s82, s8
	s_cbranch_scc0 .LBB0_139
	s_mov_b32 s1, s8
	s_branch .LBB0_147

	.amdhsa_kernel _Z14fwd_megakernel6Params
		.amdhsa_group_segment_fixed_size 0
		.amdhsa_private_segment_fixed_size 0
		.amdhsa_kernarg_size 488
		.amdhsa_user_sgpr_count 2
		.amdhsa_user_sgpr_dispatch_ptr 0
		.amdhsa_user_sgpr_queue_ptr 0
		.amdhsa_user_sgpr_kernarg_segment_ptr 1
		.amdhsa_user_sgpr_dispatch_id 0
		.amdhsa_user_sgpr_kernarg_preload_length 0
		.amdhsa_user_sgpr_kernarg_preload_offset 0
		.amdhsa_user_sgpr_private_segment_size 0
		.amdhsa_uses_dynamic_stack 0
		.amdhsa_enable_private_segment 0
		.amdhsa_system_sgpr_workgroup_id_x 1
		.amdhsa_system_sgpr_workgroup_id_y 0
		.amdhsa_system_sgpr_workgroup_id_z 0
		.amdhsa_system_sgpr_workgroup_info 0
		.amdhsa_system_vgpr_workitem_id 2
		.amdhsa_next_free_vgpr 256
		.amdhsa_next_free_sgpr 98
		.amdhsa_accum_offset 256
		.amdhsa_reserve_vcc 1
		.amdhsa_float_round_mode_32 0
		.amdhsa_float_round_mode_16_64 0
		.amdhsa_float_denorm_mode_32 3
		.amdhsa_float_denorm_mode_16_64 3
		.amdhsa_dx10_clamp 1
		.amdhsa_ieee_mode 1
		.amdhsa_fp16_overflow 0
		.amdhsa_tg_split 0
		.amdhsa_exception_fp_ieee_invalid_op 0
		.amdhsa_exception_fp_denorm_src 0
		.amdhsa_exception_fp_ieee_div_zero 0
		.amdhsa_exception_fp_ieee_overflow 0
		.amdhsa_exception_fp_ieee_underflow 0
		.amdhsa_exception_fp_ieee_inexact 0
		.amdhsa_exception_int_div_zero 0
	.end_amdhsa_kernel

amdhsa.kernels:
  - .agpr_count:     0
    .args:
      - .offset:         0
        .size:           232
        .value_kind:     by_value
      - .offset:         232
        .size:           4
        .value_kind:     hidden_block_count_x
      - .offset:         236
        .size:           4
        .value_kind:     hidden_block_count_y
      - .offset:         240
        .size:           4
        .value_kind:     hidden_block_count_z
      - .offset:         244
        .size:           2
        .value_kind:     hidden_group_size_x
      - .offset:         246
        .size:           2
        .value_kind:     hidden_group_size_y
      - .offset:         248
        .size:           2
        .value_kind:     hidden_group_size_z
      - .offset:         250
        .size:           2
        .value_kind:     hidden_remainder_x
      - .offset:         252
        .size:           2
        .value_kind:     hidden_remainder_y
      - .offset:         254
        .size:           2
        .value_kind:     hidden_remainder_z
      - .offset:         272
        .size:           8
        .value_kind:     hidden_global_offset_x
      - .offset:         280
        .size:           8
        .value_kind:     hidden_global_offset_y
      - .offset:         288
        .size:           8
        .value_kind:     hidden_global_offset_z
      - .offset:         296
        .size:           2
        .value_kind:     hidden_grid_dims
      - .offset:         320
        .size:           8
        .value_kind:     hidden_multigrid_sync_arg
      - .offset:         352
        .size:           4
        .value_kind:     hidden_dynamic_lds_size
    .group_segment_fixed_size: 0
    .kernarg_segment_align: 8
    .kernarg_segment_size: 488
    .language:       OpenCL C
    .language_version:
      - 2
      - 0
    .max_flat_workgroup_size: 512
    .name:           _Z14fwd_megakernel6Params
    .private_segment_fixed_size: 0
    .sgpr_count:     104
    .sgpr_spill_count: 18
    .symbol:         _Z14fwd_megakernel6Params.kd
    .uniform_work_group_size: 1
    .uses_dynamic_stack: false
    .vgpr_count:     256
    .vgpr_spill_count: 0
    .wavefront_size: 64
